# IN GEMM: first K-iteration peeled, first MFMA per accumulator takes SrcC=0, all per-tile accumulator zeroing v_movs removed from the epilogues
# baseline (speedup 1.0000x reference)
.LBB0_139:
	s_ashr_i32 s27, s26, 31
	s_lshl_b64 s[0:1], s[26:27], 20
	s_add_u32 s86, s16, s0
	s_addc_u32 s87, s17, s1
	s_and_b64 s[0:1], s[6:7], exec
	s_cselect_b32 s0, s87, s11
	s_cselect_b32 s1, s86, s10
	s_ashr_i32 s25, s24, 31
	s_lshl_b64 s[14:15], s[24:25], 20
	s_add_u32 s90, s19, s14
	s_addc_u32 s91, s28, s15
	s_and_b64 s[14:15], s[6:7], exec
	s_cselect_b32 s25, s91, s9
	s_cselect_b32 s27, s90, s8
	s_add_u32 s57, s8, 0x100
	s_addc_u32 s58, s9, 0
	s_add_u32 s8, s10, 0x80080
	v_mov_b32_e32 v2, 0
	s_addc_u32 s9, s11, 0
	s_mov_b32 s59, -2
	s_cmp_lg_u32 s54, 1
	s_branch .Lin_zskip
	v_mov_b32_e32 v3, v2
	v_mov_b32_e32 v4, v2
	v_mov_b32_e32 v5, v2
	v_mov_b32_e32 v6, v2
	v_mov_b32_e32 v7, v2
	v_mov_b32_e32 v8, v2
	v_mov_b32_e32 v9, v2
	v_mov_b32_e32 v18, v2
	v_mov_b32_e32 v19, v2
	v_mov_b32_e32 v20, v2
	v_mov_b32_e32 v21, v2
	v_mov_b32_e32 v22, v2
	v_mov_b32_e32 v23, v2
	v_mov_b32_e32 v24, v2
	v_mov_b32_e32 v25, v2
	v_mov_b32_e32 v34, v2
	v_mov_b32_e32 v35, v2
	v_mov_b32_e32 v36, v2
	v_mov_b32_e32 v37, v2
	v_mov_b32_e32 v38, v2
	v_mov_b32_e32 v39, v2
	v_mov_b32_e32 v40, v2
	v_mov_b32_e32 v41, v2
	v_mov_b32_e32 v50, v2
	v_mov_b32_e32 v51, v2
	v_mov_b32_e32 v52, v2
	v_mov_b32_e32 v53, v2
	v_mov_b32_e32 v54, v2
	v_mov_b32_e32 v55, v2
	v_mov_b32_e32 v56, v2
	v_mov_b32_e32 v57, v2
	v_mov_b32_e32 v10, v2
	v_mov_b32_e32 v11, v2
	v_mov_b32_e32 v12, v2
	v_mov_b32_e32 v13, v2
	v_mov_b32_e32 v14, v2
	v_mov_b32_e32 v15, v2
	v_mov_b32_e32 v16, v2
	v_mov_b32_e32 v17, v2
	v_mov_b32_e32 v26, v2
	v_mov_b32_e32 v27, v2
	v_mov_b32_e32 v28, v2
	v_mov_b32_e32 v29, v2
	v_mov_b32_e32 v30, v2
	v_mov_b32_e32 v31, v2
	v_mov_b32_e32 v32, v2
	v_mov_b32_e32 v33, v2
	v_mov_b32_e32 v42, v2
	v_mov_b32_e32 v43, v2
	v_mov_b32_e32 v44, v2
	v_mov_b32_e32 v45, v2
	v_mov_b32_e32 v46, v2
	v_mov_b32_e32 v47, v2
	v_mov_b32_e32 v48, v2
	v_mov_b32_e32 v49, v2
	v_mov_b32_e32 v58, v2
	v_mov_b32_e32 v59, v2
	v_mov_b32_e32 v60, v2
	v_mov_b32_e32 v61, v2
	v_mov_b32_e32 v62, v2
	v_mov_b32_e32 v63, v2
	v_mov_b32_e32 v64, v2
	v_mov_b32_e32 v65, v2
	v_mov_b32_e32 v66, v2
	v_mov_b32_e32 v67, v2
	v_mov_b32_e32 v68, v2
	v_mov_b32_e32 v69, v2
	v_mov_b32_e32 v70, v2
	v_mov_b32_e32 v71, v2
	v_mov_b32_e32 v72, v2
	v_mov_b32_e32 v73, v2
	v_mov_b32_e32 v82, v2
	v_mov_b32_e32 v83, v2
	v_mov_b32_e32 v84, v2
	v_mov_b32_e32 v85, v2
	v_mov_b32_e32 v86, v2
	v_mov_b32_e32 v87, v2
	v_mov_b32_e32 v88, v2
	v_mov_b32_e32 v89, v2
	v_mov_b32_e32 v98, v2
	v_mov_b32_e32 v99, v2
	v_mov_b32_e32 v100, v2
	v_mov_b32_e32 v101, v2
	v_mov_b32_e32 v102, v2
	v_mov_b32_e32 v103, v2
	v_mov_b32_e32 v104, v2
	v_mov_b32_e32 v105, v2
	v_mov_b32_e32 v114, v2
	v_mov_b32_e32 v115, v2
	v_mov_b32_e32 v116, v2
	v_mov_b32_e32 v117, v2
	v_mov_b32_e32 v118, v2
	v_mov_b32_e32 v119, v2
	v_mov_b32_e32 v120, v2
	v_mov_b32_e32 v121, v2
	v_mov_b32_e32 v74, v2
	v_mov_b32_e32 v75, v2
	v_mov_b32_e32 v76, v2
	v_mov_b32_e32 v77, v2
	v_mov_b32_e32 v78, v2
	v_mov_b32_e32 v79, v2
	v_mov_b32_e32 v80, v2
	v_mov_b32_e32 v81, v2
	v_mov_b32_e32 v90, v2
	v_mov_b32_e32 v91, v2
	v_mov_b32_e32 v92, v2
	v_mov_b32_e32 v93, v2
	v_mov_b32_e32 v94, v2
	v_mov_b32_e32 v95, v2
	v_mov_b32_e32 v96, v2
	v_mov_b32_e32 v97, v2
	v_mov_b32_e32 v106, v2
	v_mov_b32_e32 v107, v2
	v_mov_b32_e32 v108, v2
	v_mov_b32_e32 v109, v2
	v_mov_b32_e32 v110, v2
	v_mov_b32_e32 v111, v2
	v_mov_b32_e32 v112, v2
	v_mov_b32_e32 v113, v2
	v_mov_b32_e32 v122, v2
	v_mov_b32_e32 v123, v2
	v_mov_b32_e32 v124, v2
	v_mov_b32_e32 v125, v2
	v_mov_b32_e32 v126, v2
	v_mov_b32_e32 v127, v2
	v_mov_b32_e32 v128, v2
	v_mov_b32_e32 v129, v2
.Lin_zskip:
	s_add_u32 s10, s8, 0xfff80080
	s_addc_u32 s11, s9, -1
	s_add_i32 s60, 0, 0x10000
	s_cmp_eq_u32 s59, 28
	s_cselect_b32 s15, s0, s11
	s_cselect_b32 s14, s1, s10
	v_add_u32_e32 v0, s60, v167
	s_cselect_b32 s11, s25, s58
	s_cselect_b32 s10, s27, s57
	s_add_i32 s62, 0, 0x14000
	ds_read_b128 v[130:133], v0
	ds_read_b128 v[158:161], v0 offset:1024
	ds_read_b128 v[162:165], v0 offset:2048
	ds_read_b128 v[170:173], v0 offset:3072
	v_add_u32_e32 v0, s62, v167
	ds_read_b128 v[174:177], v0
	ds_read_b128 v[178:181], v0 offset:1024
	ds_read_b128 v[182:185], v0 offset:2048
	ds_read_b128 v[186:189], v0 offset:3072
	s_mov_b32 m0, s52
	s_nop 0
	global_load_lds_dwordx4 v140, s[74:75]
	s_mov_b32 m0, s53
	s_nop 0
	global_load_lds_dwordx4 v136, s[74:75]
	s_add_i32 m0, s48, 0xc000
	ds_read_b128 v[190:193], v169
	ds_read_b128 v[194:197], v169 offset:1024
	ds_read_b128 v[198:201], v169 offset:2048
	ds_read_b128 v[216:219], v169 offset:3072
	ds_read_b128 v[220:223], v169 offset:4096
	ds_read_b128 v[224:227], v169 offset:5120
	ds_read_b128 v[228:231], v169 offset:6144
	ds_read_b128 v[232:235], v169 offset:7168
	global_load_lds_dwordx4 v156, s[8:9]
	s_add_i32 m0, s48, 0xe000
	s_nop 0
	global_load_lds_dwordx4 v146, s[8:9]
	s_waitcnt vmcnt(8)
	s_waitcnt lgkmcnt(0)
	s_barrier
	s_setprio 1
	s_waitcnt lgkmcnt(0)
	v_mfma_f32_16x16x32_bf16 v[126:129], v[130:133], v[190:193], 0
	v_mfma_f32_16x16x32_bf16 v[122:125], v[162:165], v[190:193], 0
	v_mfma_f32_16x16x32_bf16 v[110:113], v[130:133], v[198:201], 0
	v_mfma_f32_16x16x32_bf16 v[106:109], v[162:165], v[198:201], 0
	v_mfma_f32_16x16x32_bf16 v[94:97], v[130:133], v[220:223], 0
	v_mfma_f32_16x16x32_bf16 v[90:93], v[162:165], v[220:223], 0
	v_mfma_f32_16x16x32_bf16 v[78:81], v[130:133], v[228:231], 0
	v_mfma_f32_16x16x32_bf16 v[74:77], v[162:165], v[228:231], 0
	v_mfma_f32_16x16x32_bf16 v[126:129], v[158:161], v[194:197], v[126:129]
	v_mfma_f32_16x16x32_bf16 v[122:125], v[170:173], v[194:197], v[122:125]
	v_mfma_f32_16x16x32_bf16 v[110:113], v[158:161], v[216:219], v[110:113]
	v_mfma_f32_16x16x32_bf16 v[106:109], v[170:173], v[216:219], v[106:109]
	v_mfma_f32_16x16x32_bf16 v[94:97], v[158:161], v[224:227], v[94:97]
	v_mfma_f32_16x16x32_bf16 v[90:93], v[170:173], v[224:227], v[90:93]
	v_mfma_f32_16x16x32_bf16 v[78:81], v[158:161], v[232:235], v[78:81]
	v_mfma_f32_16x16x32_bf16 v[74:77], v[170:173], v[232:235], v[74:77]
	s_setprio 0
	s_setprio 1
	v_mfma_f32_16x16x32_bf16 v[118:121], v[174:177], v[190:193], 0
	v_mfma_f32_16x16x32_bf16 v[114:117], v[182:185], v[190:193], 0
	v_mfma_f32_16x16x32_bf16 v[102:105], v[174:177], v[198:201], 0
	v_mfma_f32_16x16x32_bf16 v[98:101], v[182:185], v[198:201], 0
	v_mfma_f32_16x16x32_bf16 v[86:89], v[174:177], v[220:223], 0
	v_mfma_f32_16x16x32_bf16 v[82:85], v[182:185], v[220:223], 0
	v_mfma_f32_16x16x32_bf16 v[70:73], v[174:177], v[228:231], 0
	v_mfma_f32_16x16x32_bf16 v[66:69], v[182:185], v[228:231], 0
	v_mfma_f32_16x16x32_bf16 v[118:121], v[178:181], v[194:197], v[118:121]
	v_mfma_f32_16x16x32_bf16 v[114:117], v[186:189], v[194:197], v[114:117]
	v_mfma_f32_16x16x32_bf16 v[102:105], v[178:181], v[216:219], v[102:105]
	v_mfma_f32_16x16x32_bf16 v[98:101], v[186:189], v[216:219], v[98:101]
	v_mfma_f32_16x16x32_bf16 v[86:89], v[178:181], v[224:227], v[86:89]
	v_mfma_f32_16x16x32_bf16 v[82:85], v[186:189], v[224:227], v[82:85]
	v_mfma_f32_16x16x32_bf16 v[70:73], v[178:181], v[232:235], v[70:73]
	v_mfma_f32_16x16x32_bf16 v[66:69], v[186:189], v[232:235], v[66:69]
	s_setprio 0
	s_barrier
	s_add_i32 s60, s60, s29
	s_add_u32 s72, s10, s44
	s_addc_u32 s73, s11, s45
	s_mov_b32 m0, s60
	ds_read_b128 v[190:193], v169 offset:16384
	ds_read_b128 v[194:197], v169 offset:17408
	ds_read_b128 v[198:201], v169 offset:18432
	ds_read_b128 v[216:219], v169 offset:19456
	ds_read_b128 v[220:223], v169 offset:20480
	ds_read_b128 v[224:227], v169 offset:21504
	ds_read_b128 v[228:231], v169 offset:22528
	ds_read_b128 v[232:235], v169 offset:23552
	global_load_lds_dwordx4 v138, s[10:11]
	s_add_i32 m0, s60, 0x2000
	s_add_u32 s60, s10, 0x80000
	s_addc_u32 s61, s11, 0
	s_add_i32 s62, s62, s29
	global_load_lds_dwordx4 v134, s[10:11]
	s_mov_b32 m0, s62
	s_add_u32 s74, s14, s44
	s_addc_u32 s75, s15, s45
	global_load_lds_dwordx4 v138, s[60:61]
	s_add_i32 m0, s62, 0x2000
	s_nop 0
	global_load_lds_dwordx4 v134, s[60:61]
	s_waitcnt vmcnt(6)
	s_waitcnt lgkmcnt(0)
	s_barrier
	s_setprio 1
	s_waitcnt lgkmcnt(0)
	v_mfma_f32_16x16x32_bf16 v[62:65], v[130:133], v[190:193], 0
	v_mfma_f32_16x16x32_bf16 v[58:61], v[162:165], v[190:193], 0
	v_mfma_f32_16x16x32_bf16 v[46:49], v[130:133], v[198:201], 0
	v_mfma_f32_16x16x32_bf16 v[42:45], v[162:165], v[198:201], 0
	v_mfma_f32_16x16x32_bf16 v[30:33], v[130:133], v[220:223], 0
	v_mfma_f32_16x16x32_bf16 v[26:29], v[162:165], v[220:223], 0
	v_mfma_f32_16x16x32_bf16 v[14:17], v[130:133], v[228:231], 0
	v_mfma_f32_16x16x32_bf16 v[10:13], v[162:165], v[228:231], 0
	v_mfma_f32_16x16x32_bf16 v[62:65], v[158:161], v[194:197], v[62:65]
	v_mfma_f32_16x16x32_bf16 v[58:61], v[170:173], v[194:197], v[58:61]
	v_mfma_f32_16x16x32_bf16 v[46:49], v[158:161], v[216:219], v[46:49]
	v_mfma_f32_16x16x32_bf16 v[42:45], v[170:173], v[216:219], v[42:45]
	v_mfma_f32_16x16x32_bf16 v[30:33], v[158:161], v[224:227], v[30:33]
	v_mfma_f32_16x16x32_bf16 v[26:29], v[170:173], v[224:227], v[26:29]
	v_mfma_f32_16x16x32_bf16 v[14:17], v[158:161], v[232:235], v[14:17]
	v_mfma_f32_16x16x32_bf16 v[10:13], v[170:173], v[232:235], v[10:13]
	s_setprio 0
	s_setprio 1
	v_mfma_f32_16x16x32_bf16 v[54:57], v[174:177], v[190:193], 0
	v_mfma_f32_16x16x32_bf16 v[50:53], v[182:185], v[190:193], 0
	v_mfma_f32_16x16x32_bf16 v[38:41], v[174:177], v[198:201], 0
	v_mfma_f32_16x16x32_bf16 v[34:37], v[182:185], v[198:201], 0
	v_mfma_f32_16x16x32_bf16 v[22:25], v[174:177], v[220:223], 0
	v_mfma_f32_16x16x32_bf16 v[18:21], v[182:185], v[220:223], 0
	v_mfma_f32_16x16x32_bf16 v[6:9], v[174:177], v[228:231], 0
	v_mfma_f32_16x16x32_bf16 v[2:5], v[182:185], v[228:231], 0
	v_mfma_f32_16x16x32_bf16 v[54:57], v[178:181], v[194:197], v[54:57]
	v_mfma_f32_16x16x32_bf16 v[50:53], v[186:189], v[194:197], v[50:53]
	v_mfma_f32_16x16x32_bf16 v[38:41], v[178:181], v[216:219], v[38:41]
	v_mfma_f32_16x16x32_bf16 v[34:37], v[186:189], v[216:219], v[34:37]
	v_mfma_f32_16x16x32_bf16 v[22:25], v[178:181], v[224:227], v[22:25]
	v_mfma_f32_16x16x32_bf16 v[18:21], v[186:189], v[224:227], v[18:21]
	v_mfma_f32_16x16x32_bf16 v[6:9], v[178:181], v[232:235], v[6:9]
	v_mfma_f32_16x16x32_bf16 v[2:5], v[186:189], v[232:235], v[2:5]
	s_setprio 0
	s_barrier
	s_add_i32 s60, 0, 0x18000
	v_add_u32_e32 v0, s60, v167
	s_add_i32 s61, 0, 0x1c000
	ds_read_b128 v[130:133], v0
	ds_read_b128 v[158:161], v0 offset:1024
	ds_read_b128 v[162:165], v0 offset:2048
	ds_read_b128 v[170:173], v0 offset:3072
	v_add_u32_e32 v0, s61, v167
	ds_read_b128 v[174:177], v0
	ds_read_b128 v[178:181], v0 offset:1024
	ds_read_b128 v[182:185], v0 offset:2048
	ds_read_b128 v[186:189], v0 offset:3072
	s_mov_b32 m0, s48
	s_nop 0
	global_load_lds_dwordx4 v140, s[14:15]
	s_mov_b32 m0, s49
	s_nop 0
	global_load_lds_dwordx4 v136, s[14:15]
	s_add_u32 s14, s14, 0x80000
	s_addc_u32 s15, s15, 0
	s_mov_b32 m0, s50
	ds_read_b128 v[190:193], v169 offset:32768
	ds_read_b128 v[194:197], v169 offset:33792
	ds_read_b128 v[198:201], v169 offset:34816
	ds_read_b128 v[216:219], v169 offset:35840
	ds_read_b128 v[220:223], v169 offset:36864
	ds_read_b128 v[224:227], v169 offset:37888
	ds_read_b128 v[228:231], v169 offset:38912
	ds_read_b128 v[232:235], v169 offset:39936
	global_load_lds_dwordx4 v140, s[14:15]
	s_mov_b32 m0, s51
	s_nop 0
	global_load_lds_dwordx4 v136, s[14:15]
	s_waitcnt vmcnt(8)
	s_waitcnt lgkmcnt(0)
	s_barrier
	s_setprio 1
	s_waitcnt lgkmcnt(0)
	v_mfma_f32_16x16x32_bf16 v[126:129], v[130:133], v[190:193], v[126:129]
	v_mfma_f32_16x16x32_bf16 v[122:125], v[162:165], v[190:193], v[122:125]
	v_mfma_f32_16x16x32_bf16 v[110:113], v[130:133], v[198:201], v[110:113]
	v_mfma_f32_16x16x32_bf16 v[106:109], v[162:165], v[198:201], v[106:109]
	v_mfma_f32_16x16x32_bf16 v[94:97], v[130:133], v[220:223], v[94:97]
	v_mfma_f32_16x16x32_bf16 v[90:93], v[162:165], v[220:223], v[90:93]
	v_mfma_f32_16x16x32_bf16 v[78:81], v[130:133], v[228:231], v[78:81]
	v_mfma_f32_16x16x32_bf16 v[74:77], v[162:165], v[228:231], v[74:77]
	v_mfma_f32_16x16x32_bf16 v[126:129], v[158:161], v[194:197], v[126:129]
	v_mfma_f32_16x16x32_bf16 v[122:125], v[170:173], v[194:197], v[122:125]
	v_mfma_f32_16x16x32_bf16 v[110:113], v[158:161], v[216:219], v[110:113]
	v_mfma_f32_16x16x32_bf16 v[106:109], v[170:173], v[216:219], v[106:109]
	v_mfma_f32_16x16x32_bf16 v[94:97], v[158:161], v[224:227], v[94:97]
	v_mfma_f32_16x16x32_bf16 v[90:93], v[170:173], v[224:227], v[90:93]
	v_mfma_f32_16x16x32_bf16 v[78:81], v[158:161], v[232:235], v[78:81]
	v_mfma_f32_16x16x32_bf16 v[74:77], v[170:173], v[232:235], v[74:77]
	s_setprio 0
	s_setprio 1
	v_mfma_f32_16x16x32_bf16 v[118:121], v[174:177], v[190:193], v[118:121]
	v_mfma_f32_16x16x32_bf16 v[114:117], v[182:185], v[190:193], v[114:117]
	v_mfma_f32_16x16x32_bf16 v[102:105], v[174:177], v[198:201], v[102:105]
	v_mfma_f32_16x16x32_bf16 v[98:101], v[182:185], v[198:201], v[98:101]
	v_mfma_f32_16x16x32_bf16 v[86:89], v[174:177], v[220:223], v[86:89]
	v_mfma_f32_16x16x32_bf16 v[82:85], v[182:185], v[220:223], v[82:85]
	v_mfma_f32_16x16x32_bf16 v[70:73], v[174:177], v[228:231], v[70:73]
	v_mfma_f32_16x16x32_bf16 v[66:69], v[182:185], v[228:231], v[66:69]
	v_mfma_f32_16x16x32_bf16 v[118:121], v[178:181], v[194:197], v[118:121]
	v_mfma_f32_16x16x32_bf16 v[114:117], v[186:189], v[194:197], v[114:117]
	v_mfma_f32_16x16x32_bf16 v[102:105], v[178:181], v[216:219], v[102:105]
	v_mfma_f32_16x16x32_bf16 v[98:101], v[186:189], v[216:219], v[98:101]
	v_mfma_f32_16x16x32_bf16 v[86:89], v[178:181], v[224:227], v[86:89]
	v_mfma_f32_16x16x32_bf16 v[82:85], v[186:189], v[224:227], v[82:85]
	v_mfma_f32_16x16x32_bf16 v[70:73], v[178:181], v[232:235], v[70:73]
	v_mfma_f32_16x16x32_bf16 v[66:69], v[186:189], v[232:235], v[66:69]
	s_setprio 0
	s_barrier
	s_add_i32 s14, s60, s29
	s_mov_b32 m0, s14
	ds_read_b128 v[190:193], v169 offset:49152
	ds_read_b128 v[194:197], v169 offset:50176
	ds_read_b128 v[198:201], v169 offset:51200
	ds_read_b128 v[216:219], v169 offset:52224
	ds_read_b128 v[220:223], v169 offset:53248
	ds_read_b128 v[224:227], v169 offset:54272
	ds_read_b128 v[228:231], v169 offset:55296
	ds_read_b128 v[232:235], v169 offset:56320
	global_load_lds_dwordx4 v138, s[72:73]
	s_add_i32 m0, s14, 0x2000
	s_add_u32 s10, s10, 0x80080
	s_addc_u32 s11, s11, 0
	s_add_i32 s14, s61, s29
	global_load_lds_dwordx4 v134, s[72:73]
	s_mov_b32 m0, s14
	s_nop 0
	global_load_lds_dwordx4 v138, s[10:11]
	s_add_i32 m0, s14, 0x2000
	s_nop 0
	global_load_lds_dwordx4 v134, s[10:11]
	s_waitcnt vmcnt(6)
	s_waitcnt lgkmcnt(0)
	s_barrier
	s_setprio 1
	s_waitcnt lgkmcnt(0)
	v_mfma_f32_16x16x32_bf16 v[62:65], v[130:133], v[190:193], v[62:65]
	v_mfma_f32_16x16x32_bf16 v[58:61], v[162:165], v[190:193], v[58:61]
	v_mfma_f32_16x16x32_bf16 v[46:49], v[130:133], v[198:201], v[46:49]
	v_mfma_f32_16x16x32_bf16 v[42:45], v[162:165], v[198:201], v[42:45]
	v_mfma_f32_16x16x32_bf16 v[30:33], v[130:133], v[220:223], v[30:33]
	v_mfma_f32_16x16x32_bf16 v[26:29], v[162:165], v[220:223], v[26:29]
	v_mfma_f32_16x16x32_bf16 v[14:17], v[130:133], v[228:231], v[14:17]
	v_mfma_f32_16x16x32_bf16 v[10:13], v[162:165], v[228:231], v[10:13]
	v_mfma_f32_16x16x32_bf16 v[62:65], v[158:161], v[194:197], v[62:65]
	v_mfma_f32_16x16x32_bf16 v[58:61], v[170:173], v[194:197], v[58:61]
	v_mfma_f32_16x16x32_bf16 v[46:49], v[158:161], v[216:219], v[46:49]
	v_mfma_f32_16x16x32_bf16 v[42:45], v[170:173], v[216:219], v[42:45]
	v_mfma_f32_16x16x32_bf16 v[30:33], v[158:161], v[224:227], v[30:33]
	v_mfma_f32_16x16x32_bf16 v[26:29], v[170:173], v[224:227], v[26:29]
	v_mfma_f32_16x16x32_bf16 v[14:17], v[158:161], v[232:235], v[14:17]
	v_mfma_f32_16x16x32_bf16 v[10:13], v[170:173], v[232:235], v[10:13]
	s_setprio 0
	s_setprio 1
	v_mfma_f32_16x16x32_bf16 v[54:57], v[174:177], v[190:193], v[54:57]
	v_mfma_f32_16x16x32_bf16 v[50:53], v[182:185], v[190:193], v[50:53]
	v_mfma_f32_16x16x32_bf16 v[38:41], v[174:177], v[198:201], v[38:41]
	v_mfma_f32_16x16x32_bf16 v[34:37], v[182:185], v[198:201], v[34:37]
	v_mfma_f32_16x16x32_bf16 v[22:25], v[174:177], v[220:223], v[22:25]
	v_mfma_f32_16x16x32_bf16 v[18:21], v[182:185], v[220:223], v[18:21]
	v_mfma_f32_16x16x32_bf16 v[6:9], v[174:177], v[228:231], v[6:9]
	v_mfma_f32_16x16x32_bf16 v[2:5], v[182:185], v[228:231], v[2:5]
	v_mfma_f32_16x16x32_bf16 v[54:57], v[178:181], v[194:197], v[54:57]
	v_mfma_f32_16x16x32_bf16 v[50:53], v[186:189], v[194:197], v[50:53]
	v_mfma_f32_16x16x32_bf16 v[38:41], v[178:181], v[216:219], v[38:41]
	v_mfma_f32_16x16x32_bf16 v[34:37], v[186:189], v[216:219], v[34:37]
	v_mfma_f32_16x16x32_bf16 v[22:25], v[178:181], v[224:227], v[22:25]
	v_mfma_f32_16x16x32_bf16 v[18:21], v[186:189], v[224:227], v[18:21]
	v_mfma_f32_16x16x32_bf16 v[6:9], v[178:181], v[232:235], v[6:9]
	v_mfma_f32_16x16x32_bf16 v[2:5], v[186:189], v[232:235], v[2:5]
	s_setprio 0
	s_barrier
	s_add_i32 s59, s59, 2
	s_add_u32 s57, s57, 0x100
	s_addc_u32 s58, s58, 0
	s_add_u32 s8, s8, 0x100
	s_addc_u32 s9, s9, 0
	s_cmp_gt_u32 s59, 29

.Lepi_fast:
	v_lshl_or_b32 v158, s55, 8, v168
	v_ashrrev_i32_e32 v159, 31, v158
	v_mov_b64_e32 v[172:173], s[12:13]
	v_mad_i64_i32 v[172:173], s[0:1], v170, s43, v[172:173]
	v_cvt_pk_bf16_f32 v126, v126, v127
	v_cvt_pk_bf16_f32 v127, v128, v129
	v_cvt_pk_bf16_f32 v128, v122, v123
	v_cvt_pk_bf16_f32 v129, v124, v125
	v_lshl_add_u64 v[172:173], v[158:159], 1, v[172:173]
	v_cvt_pk_bf16_f32 v118, v118, v119
	v_cvt_pk_bf16_f32 v119, v120, v121
	v_cvt_pk_bf16_f32 v120, v114, v115
	v_cvt_pk_bf16_f32 v121, v116, v117
	global_store_dwordx4 v[172:173], v[126:129], off sc1 nt
	global_store_dwordx4 v[172:173], v[118:121], off offset:256 sc1 nt
	v_add_u32_e32 v174, 16, v170
	v_mov_b64_e32 v[172:173], s[12:13]
	v_mad_i64_i32 v[172:173], s[0:1], v174, s43, v[172:173]
	v_cvt_pk_bf16_f32 v110, v110, v111
	v_cvt_pk_bf16_f32 v111, v112, v113
	v_cvt_pk_bf16_f32 v112, v106, v107
	v_cvt_pk_bf16_f32 v113, v108, v109
	v_lshl_add_u64 v[172:173], v[158:159], 1, v[172:173]
	v_cvt_pk_bf16_f32 v102, v102, v103
	v_cvt_pk_bf16_f32 v103, v104, v105
	v_cvt_pk_bf16_f32 v104, v98, v99
	v_cvt_pk_bf16_f32 v105, v100, v101
	global_store_dwordx4 v[172:173], v[110:113], off sc1 nt
	global_store_dwordx4 v[172:173], v[102:105], off offset:256 sc1 nt
	v_add_u32_e32 v174, 32, v170
	v_mov_b64_e32 v[172:173], s[12:13]
	v_mad_i64_i32 v[172:173], s[0:1], v174, s43, v[172:173]
	v_cvt_pk_bf16_f32 v94, v94, v95
	v_cvt_pk_bf16_f32 v95, v96, v97
	v_cvt_pk_bf16_f32 v96, v90, v91
	v_cvt_pk_bf16_f32 v97, v92, v93
	v_lshl_add_u64 v[172:173], v[158:159], 1, v[172:173]
	v_cvt_pk_bf16_f32 v86, v86, v87
	v_cvt_pk_bf16_f32 v87, v88, v89
	v_cvt_pk_bf16_f32 v88, v82, v83
	v_cvt_pk_bf16_f32 v89, v84, v85
	global_store_dwordx4 v[172:173], v[94:97], off sc1 nt
	global_store_dwordx4 v[172:173], v[86:89], off offset:256 sc1 nt
	v_add_u32_e32 v174, 48, v170
	v_mov_b64_e32 v[172:173], s[12:13]
	v_mad_i64_i32 v[172:173], s[0:1], v174, s43, v[172:173]
	v_cvt_pk_bf16_f32 v78, v78, v79
	v_cvt_pk_bf16_f32 v79, v80, v81
	v_cvt_pk_bf16_f32 v80, v74, v75
	v_cvt_pk_bf16_f32 v81, v76, v77
	v_lshl_add_u64 v[172:173], v[158:159], 1, v[172:173]
	v_cvt_pk_bf16_f32 v70, v70, v71
	v_cvt_pk_bf16_f32 v71, v72, v73
	v_cvt_pk_bf16_f32 v72, v66, v67
	v_cvt_pk_bf16_f32 v73, v68, v69
	global_store_dwordx4 v[172:173], v[78:81], off sc1 nt
	global_store_dwordx4 v[172:173], v[70:73], off offset:256 sc1 nt
	v_add_u32_e32 v174, 0x80, v170
	v_mov_b64_e32 v[172:173], s[12:13]
	v_mad_i64_i32 v[172:173], s[0:1], v174, s43, v[172:173]
	v_cvt_pk_bf16_f32 v62, v62, v63
	v_cvt_pk_bf16_f32 v63, v64, v65
	v_cvt_pk_bf16_f32 v64, v58, v59
	v_cvt_pk_bf16_f32 v65, v60, v61
	v_lshl_add_u64 v[172:173], v[158:159], 1, v[172:173]
	v_cvt_pk_bf16_f32 v54, v54, v55
	v_cvt_pk_bf16_f32 v55, v56, v57
	v_cvt_pk_bf16_f32 v56, v50, v51
	v_cvt_pk_bf16_f32 v57, v52, v53
	global_store_dwordx4 v[172:173], v[62:65], off sc1 nt
	global_store_dwordx4 v[172:173], v[54:57], off offset:256 sc1 nt
	v_add_u32_e32 v174, 0x90, v170
	v_mov_b64_e32 v[172:173], s[12:13]
	v_mad_i64_i32 v[172:173], s[0:1], v174, s43, v[172:173]
	v_cvt_pk_bf16_f32 v46, v46, v47
	v_cvt_pk_bf16_f32 v47, v48, v49
	v_cvt_pk_bf16_f32 v48, v42, v43
	v_cvt_pk_bf16_f32 v49, v44, v45
	v_lshl_add_u64 v[172:173], v[158:159], 1, v[172:173]
	v_cvt_pk_bf16_f32 v38, v38, v39
	v_cvt_pk_bf16_f32 v39, v40, v41
	v_cvt_pk_bf16_f32 v40, v34, v35
	v_cvt_pk_bf16_f32 v41, v36, v37
	global_store_dwordx4 v[172:173], v[46:49], off sc1 nt
	global_store_dwordx4 v[172:173], v[38:41], off offset:256 sc1 nt
	v_add_u32_e32 v174, 0xa0, v170
	v_mov_b64_e32 v[172:173], s[12:13]
	v_mad_i64_i32 v[172:173], s[0:1], v174, s43, v[172:173]
	v_cvt_pk_bf16_f32 v30, v30, v31
	v_cvt_pk_bf16_f32 v31, v32, v33
	v_cvt_pk_bf16_f32 v32, v26, v27
	v_cvt_pk_bf16_f32 v33, v28, v29
	v_lshl_add_u64 v[172:173], v[158:159], 1, v[172:173]
	v_cvt_pk_bf16_f32 v22, v22, v23
	v_cvt_pk_bf16_f32 v23, v24, v25
	v_cvt_pk_bf16_f32 v24, v18, v19
	v_cvt_pk_bf16_f32 v25, v20, v21
	global_store_dwordx4 v[172:173], v[30:33], off sc1 nt
	global_store_dwordx4 v[172:173], v[22:25], off offset:256 sc1 nt
	v_add_u32_e32 v174, 0xb0, v170
	v_mov_b64_e32 v[172:173], s[12:13]
	v_mad_i64_i32 v[172:173], s[0:1], v174, s43, v[172:173]
	v_cvt_pk_bf16_f32 v14, v14, v15
	v_cvt_pk_bf16_f32 v15, v16, v17
	v_cvt_pk_bf16_f32 v16, v10, v11
	v_cvt_pk_bf16_f32 v17, v12, v13
	v_lshl_add_u64 v[172:173], v[158:159], 1, v[172:173]
	v_cvt_pk_bf16_f32 v6, v6, v7
	v_cvt_pk_bf16_f32 v7, v8, v9
	v_cvt_pk_bf16_f32 v8, v2, v3
	v_cvt_pk_bf16_f32 v9, v4, v5
	global_store_dwordx4 v[172:173], v[14:17], off sc1 nt
	global_store_dwordx4 v[172:173], v[6:9], off offset:256 sc1 nt
	s_nop 1
	s_branch .Lepi_join
